# grid barriers 1..10: arrival counter sharded over 8 words (workgroup adds to word bx&7, 8 lanes poll the 8 words and sum) to cut atomic serialization
# speedup vs baseline: 1.0278x; 1.0074x over previous
; #define LAS __attribute__((address_space(3)))
; __global__ void __launch_bounds__(512) fwd_mega(Args a) {
;     extern __shared__ __attribute__((aligned(16))) unsigned char lds_raw[];
;     LAS unsigned char* lds = (LAS unsigned char*)lds_raw;
;     cg::grid_group grid = cg::this_grid();
;     const int tid = threadIdx.x, lane = tid & 63, wave = __builtin_amdgcn_readfirstlane(tid >> 6);
;     const int G = gridDim.x, bx = blockIdx.x;
;     const int vcu = (G % 8 == 0) ? (bx % 8) * (G / 8) + bx / 8 : bx;
;     unsigned char* ws = a.ws;
_Z8fwd_mega4Args:
	s_load_dwordx16 s[72:87], s[0:1], 0x0
	s_load_dwordx8 s[24:31], s[0:1], 0x80
	s_load_dwordx4 s[52:55], s[0:1], 0xa0
	s_load_dword s3, s[0:1], 0xb0
	s_add_u32 s58, s0, 0xb0
	s_mov_b32 s60, s2
	s_addc_u32 s59, s1, 0
	v_and_b32_e32 v162, 0x3ff, v0
	s_waitcnt lgkmcnt(0)
	s_cmp_eq_u32 s60, 0
	s_cbranch_scc0 .Lsm_init_done
	v_and_b32_e32 v254, 7, v162
	v_lshlrev_b32_e32 v254, 8, v254
	v_add_u32_e32 v254, 0x400, v254
	v_mov_b32_e32 v255, 0
	global_store_dword v254, v255, s[52:53]

; __global__ void __launch_bounds__(512) fwd_mega(Args a) {
;     ...
;     SEAM(1);
.LBB0_170:
	s_cmp_gt_i32 s55, 2
	s_cselect_b64 s[0:1], -1, 0
	s_and_b64 s[4:5], s[20:21], s[0:1]
	s_andn2_b64 vcc, exec, s[4:5]
	s_cbranch_vccnz .LBB0_186
	v_readlane_b32 s8, v253, 42
	v_readlane_b32 s9, v253, 43
	s_waitcnt vmcnt(0) lgkmcnt(0)
	s_barrier
	v_readfirstlane_b32 s98, v162
	s_nop 3
	s_cmp_lt_u32 s98, 64
	s_cbranch_scc0 .Lsm1_wait
	buffer_wbl2 sc1
	s_waitcnt vmcnt(0)
	s_mov_b64 vcc, exec
	s_mov_b64 exec, 1
	s_and_b32 s98, s60, 7
	s_lshl_b32 s98, s98, 8
	s_add_u32 s98, s98, 0x400
	v_mov_b32_e32 v254, s98
	v_mov_b32_e32 v255, 1
	global_atomic_add v254, v255, s[52:53]
	s_mov_b64 exec, 0xff
	v_mbcnt_lo_u32_b32 v254, -1, 0
	v_lshlrev_b32_e32 v254, 8, v254
	v_add_u32_e32 v254, 0x400, v254
	s_lshr_b32 s99, s56, 3
	s_mul_i32 s99, s99, 1
	s_mov_b32 s100, 0
.Lsm1_poll:
	global_load_dword v255, v254, s[52:53] sc1
	s_waitcnt vmcnt(0)
	v_readlane_b32 s98, v255, 0
	v_readlane_b32 s101, v255, 1
	s_nop 3
	s_add_u32 s98, s98, s101
	v_readlane_b32 s101, v255, 2
	s_nop 3
	s_add_u32 s98, s98, s101
	v_readlane_b32 s101, v255, 3
	s_nop 3
	s_add_u32 s98, s98, s101
	v_readlane_b32 s101, v255, 4
	s_nop 3
	s_add_u32 s98, s98, s101
	v_readlane_b32 s101, v255, 5
	s_nop 3
	s_add_u32 s98, s98, s101
	v_readlane_b32 s101, v255, 6
	s_nop 3
	s_add_u32 s98, s98, s101
	v_readlane_b32 s101, v255, 7
	s_nop 3
	s_add_u32 s98, s98, s101
	s_cmp_ge_u32 s98, s99
	s_cbranch_scc1 .Lsm1_done
	s_add_u32 s100, s100, 1
	s_cmp_lt_u32 s100, 0x4000
	s_cbranch_scc0 .Lsm1_done
	s_sleep 1
	s_branch .Lsm1_poll

; __global__ void __launch_bounds__(512) fwd_mega(Args a) {
;     ...
;     SEAM(2);
.LBB0_285:
	s_cmp_gt_i32 s55, 3
	s_cselect_b64 s[0:1], -1, 0
	s_and_b64 s[4:5], s[12:13], s[0:1]
	v_readlane_b32 s92, v253, 42
	s_andn2_b64 vcc, exec, s[4:5]
	v_readlane_b32 s93, v253, 43
	s_cbranch_vccnz .LBB0_301
	v_readlane_b32 s6, v253, 48
	s_waitcnt vmcnt(0) lgkmcnt(0)
	s_barrier
	v_readfirstlane_b32 s98, v162
	s_nop 3
	s_cmp_lt_u32 s98, 64
	s_cbranch_scc0 .Lsm2_wait
	buffer_wbl2 sc1
	s_waitcnt vmcnt(0)
	s_mov_b64 vcc, exec
	s_mov_b64 exec, 1
	s_and_b32 s98, s60, 7
	s_lshl_b32 s98, s98, 8
	s_add_u32 s98, s98, 0x400
	v_mov_b32_e32 v254, s98
	v_mov_b32_e32 v255, 1
	global_atomic_add v254, v255, s[52:53]
	s_mov_b64 exec, 0xff
	v_mbcnt_lo_u32_b32 v254, -1, 0
	v_lshlrev_b32_e32 v254, 8, v254
	v_add_u32_e32 v254, 0x400, v254
	s_lshr_b32 s99, s56, 3
	s_mul_i32 s99, s99, 2
	s_mov_b32 s100, 0

; __global__ void __launch_bounds__(512) fwd_mega(Args a) {
;     ...
;     SEAM(3);
.LBB0_682:
	s_cmp_gt_i32 s55, 4
	s_cselect_b64 s[0:1], -1, 0
	s_and_b64 s[4:5], s[44:45], s[0:1]
	v_readlane_b32 s76, v253, 26
	s_andn2_b64 vcc, exec, s[4:5]
	v_readlane_b32 s77, v253, 27
	v_readlane_b32 s80, v253, 30
	v_readlane_b32 s81, v253, 31
	v_readlane_b32 s82, v253, 32
	v_readlane_b32 s83, v253, 33
	v_readlane_b32 s84, v253, 34
	v_readlane_b32 s85, v253, 35
	v_readlane_b32 s94, v253, 48
	v_readlane_b32 s78, v253, 28
	v_readlane_b32 s79, v253, 29
	v_readlane_b32 s86, v253, 36
	v_readlane_b32 s87, v253, 37
	v_readlane_b32 s88, v253, 38
	v_readlane_b32 s89, v253, 39
	v_readlane_b32 s90, v253, 40
	v_readlane_b32 s91, v253, 41
	s_cbranch_vccnz .LBB0_698
	s_waitcnt vmcnt(0) lgkmcnt(0)
	s_barrier
	v_readfirstlane_b32 s98, v162
	s_nop 3
	s_cmp_lt_u32 s98, 64
	s_cbranch_scc0 .Lsm3_wait
	buffer_wbl2 sc1
	s_waitcnt vmcnt(0)
	s_mov_b64 vcc, exec
	s_mov_b64 exec, 1
	s_and_b32 s98, s60, 7
	s_lshl_b32 s98, s98, 8
	s_add_u32 s98, s98, 0x400
	v_mov_b32_e32 v254, s98
	v_mov_b32_e32 v255, 1
	global_atomic_add v254, v255, s[52:53]
	s_mov_b64 exec, 0xff
	v_mbcnt_lo_u32_b32 v254, -1, 0
	v_lshlrev_b32_e32 v254, 8, v254
	v_add_u32_e32 v254, 0x400, v254
	s_lshr_b32 s99, s56, 3
	s_mul_i32 s99, s99, 3
	s_mov_b32 s100, 0

; __global__ void __launch_bounds__(512) fwd_mega(Args a) {
;     ...
;     SEAM(4);
.LBB0_723:
	s_cmp_gt_i32 s55, 5
	s_cselect_b64 s[0:1], -1, 0
	s_and_b64 s[4:5], s[4:5], s[0:1]
	s_andn2_b64 vcc, exec, s[4:5]
	s_cbranch_vccnz .LBB0_739
	s_waitcnt vmcnt(0) lgkmcnt(0)
	s_barrier
	v_readfirstlane_b32 s98, v162
	s_nop 3
	s_cmp_lt_u32 s98, 64
	s_cbranch_scc0 .Lsm4_wait
	buffer_wbl2 sc1
	s_waitcnt vmcnt(0)
	s_mov_b64 vcc, exec
	s_mov_b64 exec, 1
	s_and_b32 s98, s60, 7
	s_lshl_b32 s98, s98, 8
	s_add_u32 s98, s98, 0x400
	v_mov_b32_e32 v254, s98
	v_mov_b32_e32 v255, 1
	global_atomic_add v254, v255, s[52:53]
	s_mov_b64 exec, 0xff
	v_mbcnt_lo_u32_b32 v254, -1, 0
	v_lshlrev_b32_e32 v254, 8, v254
	v_add_u32_e32 v254, 0x400, v254
	s_lshr_b32 s99, s56, 3
	s_mul_i32 s99, s99, 4
	s_mov_b32 s100, 0

; __global__ void __launch_bounds__(512) fwd_mega(Args a) {
;     ...
;     SEAM(5);
.LBB0_788:
	s_cmp_gt_i32 s55, 6
	s_cselect_b64 s[0:1], -1, 0
	s_and_b64 s[4:5], s[4:5], s[0:1]
	s_andn2_b64 vcc, exec, s[4:5]
	s_cbranch_vccnz .LBB0_804
	s_waitcnt vmcnt(0) lgkmcnt(0)
	s_barrier
	v_readfirstlane_b32 s98, v162
	s_nop 3
	s_cmp_lt_u32 s98, 64
	s_cbranch_scc0 .Lsm5_wait
	buffer_wbl2 sc1
	s_waitcnt vmcnt(0)
	s_mov_b64 vcc, exec
	s_mov_b64 exec, 1
	s_and_b32 s98, s60, 7
	s_lshl_b32 s98, s98, 8
	s_add_u32 s98, s98, 0x400
	v_mov_b32_e32 v254, s98
	v_mov_b32_e32 v255, 1
	global_atomic_add v254, v255, s[52:53]
	s_mov_b64 exec, 0xff
	v_mbcnt_lo_u32_b32 v254, -1, 0
	v_lshlrev_b32_e32 v254, 8, v254
	v_add_u32_e32 v254, 0x400, v254
	s_lshr_b32 s99, s56, 3
	s_mul_i32 s99, s99, 5
	s_mov_b32 s100, 0

; __global__ void __launch_bounds__(512) fwd_mega(Args a) {
;     ...
;     SEAM(6);
.LBB0_863:
	s_cmp_gt_i32 s55, 7
	s_cselect_b64 s[0:1], -1, 0
	s_and_b64 s[4:5], s[18:19], s[0:1]
	s_andn2_b64 vcc, exec, s[4:5]
	s_cbranch_vccnz .LBB0_879
	s_waitcnt vmcnt(0) lgkmcnt(0)
	s_barrier
	v_readfirstlane_b32 s98, v162
	s_nop 3
	s_cmp_lt_u32 s98, 64
	s_cbranch_scc0 .Lsm6_wait
	buffer_wbl2 sc1
	s_waitcnt vmcnt(0)
	s_mov_b64 vcc, exec
	s_mov_b64 exec, 1
	s_and_b32 s98, s60, 7
	s_lshl_b32 s98, s98, 8
	s_add_u32 s98, s98, 0x400
	v_mov_b32_e32 v254, s98
	v_mov_b32_e32 v255, 1
	global_atomic_add v254, v255, s[52:53]
	s_mov_b64 exec, 0xff
	v_mbcnt_lo_u32_b32 v254, -1, 0
	v_lshlrev_b32_e32 v254, 8, v254
	v_add_u32_e32 v254, 0x400, v254
	s_lshr_b32 s99, s56, 3
	s_mul_i32 s99, s99, 6
	s_mov_b32 s100, 0

; __global__ void __launch_bounds__(512) fwd_mega(Args a) {
;     ...
;     SEAM(7);
.LBB0_882:
	s_cmp_gt_i32 s55, 8
	s_cselect_b64 s[0:1], -1, 0
	s_and_b64 s[4:5], s[4:5], s[0:1]
	v_readlane_b32 s68, v253, 24
	s_andn2_b64 vcc, exec, s[4:5]
	v_readlane_b32 s69, v253, 25
	s_cbranch_vccnz .LBB0_898
	s_waitcnt vmcnt(0) lgkmcnt(0)
	s_barrier
	v_readfirstlane_b32 s98, v162
	s_nop 3
	s_cmp_lt_u32 s98, 64
	s_cbranch_scc0 .Lsm7_wait
	buffer_wbl2 sc1
	s_waitcnt vmcnt(0)
	s_mov_b64 vcc, exec
	s_mov_b64 exec, 1
	s_and_b32 s98, s60, 7
	s_lshl_b32 s98, s98, 8
	s_add_u32 s98, s98, 0x400
	v_mov_b32_e32 v254, s98
	v_mov_b32_e32 v255, 1
	global_atomic_add v254, v255, s[52:53]
	s_mov_b64 exec, 0xff
	v_mbcnt_lo_u32_b32 v254, -1, 0
	v_lshlrev_b32_e32 v254, 8, v254
	v_add_u32_e32 v254, 0x400, v254
	s_lshr_b32 s99, s56, 3
	s_mul_i32 s99, s99, 7
	s_mov_b32 s100, 0

; __global__ void __launch_bounds__(512) fwd_mega(Args a) {
;     ...
;     SEAM(8);
.LBB0_927:
	s_cmp_gt_i32 s55, 9
	s_cselect_b64 s[0:1], -1, 0
	s_and_b64 s[4:5], s[22:23], s[0:1]
	s_andn2_b64 vcc, exec, s[4:5]
	s_cbranch_vccnz .LBB0_943
	s_waitcnt vmcnt(0) lgkmcnt(0)
	s_barrier
	v_readfirstlane_b32 s98, v162
	s_nop 3
	s_cmp_lt_u32 s98, 64
	s_cbranch_scc0 .Lsm8_wait
	buffer_wbl2 sc1
	s_waitcnt vmcnt(0)
	s_mov_b64 vcc, exec
	s_mov_b64 exec, 1
	s_and_b32 s98, s60, 7
	s_lshl_b32 s98, s98, 8
	s_add_u32 s98, s98, 0x400
	v_mov_b32_e32 v254, s98
	v_mov_b32_e32 v255, 1
	global_atomic_add v254, v255, s[52:53]
	s_mov_b64 exec, 0xff
	v_mbcnt_lo_u32_b32 v254, -1, 0
	v_lshlrev_b32_e32 v254, 8, v254
	v_add_u32_e32 v254, 0x400, v254
	s_lshr_b32 s99, s56, 3
	s_mul_i32 s99, s99, 8
	s_mov_b32 s100, 0

; __global__ void __launch_bounds__(512) fwd_mega(Args a) {
;     ...
;     SEAM(9);
.LBB0_954:
	s_cmp_gt_i32 s55, 10
	s_cselect_b64 s[0:1], -1, 0
	s_and_b64 s[4:5], s[4:5], s[0:1]
	s_andn2_b64 vcc, exec, s[4:5]
	s_cbranch_vccnz .LBB0_970
	s_waitcnt vmcnt(0) lgkmcnt(0)
	s_barrier
	v_readfirstlane_b32 s98, v162
	s_nop 3
	s_cmp_lt_u32 s98, 64
	s_cbranch_scc0 .Lsm9_wait
	buffer_wbl2 sc1
	s_waitcnt vmcnt(0)
	s_mov_b64 vcc, exec
	s_mov_b64 exec, 1
	s_and_b32 s98, s60, 7
	s_lshl_b32 s98, s98, 8
	s_add_u32 s98, s98, 0x400
	v_mov_b32_e32 v254, s98
	v_mov_b32_e32 v255, 1
	global_atomic_add v254, v255, s[52:53]
	s_mov_b64 exec, 0xff
	v_mbcnt_lo_u32_b32 v254, -1, 0
	v_lshlrev_b32_e32 v254, 8, v254
	v_add_u32_e32 v254, 0x400, v254
	s_lshr_b32 s99, s56, 3
	s_mul_i32 s99, s99, 9
	s_mov_b32 s100, 0

; __global__ void __launch_bounds__(512) fwd_mega(Args a) {
;     ...
;     SEAM(10);
.LBB0_1033:
	s_cmp_gt_i32 s55, 11
	s_cselect_b64 s[0:1], -1, 0
	s_and_b64 s[2:3], s[8:9], s[0:1]
	s_andn2_b64 vcc, exec, s[2:3]
	s_cbranch_vccnz .LBB0_1049
	s_waitcnt vmcnt(0) lgkmcnt(0)
	s_barrier
	v_readfirstlane_b32 s98, v162
	s_nop 3
	s_cmp_lt_u32 s98, 64
	s_cbranch_scc0 .Lsm10_wait
	buffer_wbl2 sc1
	s_waitcnt vmcnt(0)
	s_mov_b64 vcc, exec
	s_mov_b64 exec, 1
	s_and_b32 s98, s60, 7
	s_lshl_b32 s98, s98, 8
	s_add_u32 s98, s98, 0x400
	v_mov_b32_e32 v254, s98
	v_mov_b32_e32 v255, 1
	global_atomic_add v254, v255, s[52:53]
	s_mov_b64 exec, 0xff
	v_mbcnt_lo_u32_b32 v254, -1, 0
	v_lshlrev_b32_e32 v254, 8, v254
	v_add_u32_e32 v254, 0x400, v254
	s_lshr_b32 s99, s56, 3
	s_mul_i32 s99, s99, 10
	s_mov_b32 s100, 0
